# add: grid-barrier non-leader L1 invalidate issued before the spin instead of after the release
# speedup vs baseline: 1.0034x; 1.0034x over previous
.LBB0_68:
	s_or_b64 exec, exec, s[6:7]
	v_cvt_f32_u32_e32 v4, v2
	s_waitcnt vmcnt(0)
	v_readfirstlane_b32 s4, v3
	v_sub_u32_e32 v3, 0, v2
	v_rcp_iflag_f32_e32 v4, v4
	v_add_u32_e32 v5, s4, v1
	v_mul_f32_e32 v4, 0x4f7ffffe, v4
	v_cvt_u32_f32_e32 v4, v4
	v_mul_lo_u32 v1, v3, v4
	v_mul_hi_u32 v1, v4, v1
	v_add_u32_e32 v1, v4, v1
	v_mul_hi_u32 v1, v5, v1
	v_mul_lo_u32 v3, v1, v2
	v_sub_u32_e32 v3, v5, v3
	v_add_u32_e32 v4, 1, v1
	v_cmp_ge_u32_e32 vcc, v3, v2
	s_nop 1
	v_cndmask_b32_e32 v1, v1, v4, vcc
	v_sub_u32_e32 v4, v3, v2
	v_cndmask_b32_e32 v3, v3, v4, vcc
	v_add_u32_e32 v4, 1, v1
	v_cmp_ge_u32_e32 vcc, v3, v2
	v_add_u32_e32 v3, 1, v5
	s_nop 0
	v_cndmask_b32_e32 v1, v1, v4, vcc
	v_mul_lo_u32 v4, v2, v1
	v_add_u32_e32 v2, v4, v2
	v_cmp_ne_u32_e32 vcc, v3, v2
	s_and_saveexec_b64 s[4:5], vcc
	s_xor_b64 s[4:5], exec, s[4:5]
	s_cbranch_execz .LBB0_82
	s_add_i32 s6, s14, 0x900
	s_mov_b32 s7, 0
	s_lshl_b64 s[6:7], s[6:7], 2
	v_readlane_b32 s8, v252, 44
	v_readlane_b32 s9, v252, 45
	s_add_u32 s10, s8, s6
	s_addc_u32 s11, s9, s7
	s_waitcnt lgkmcnt(0)
	v_mov_b32_e32 v0, 0
	buffer_inv sc1
	global_load_dword v2, v0, s[10:11] sc1
	s_waitcnt vmcnt(0)
	v_cmp_eq_u32_e32 vcc, v2, v1
	s_and_saveexec_b64 s[6:7], vcc
	s_cbranch_execz .LBB0_81
	s_load_dwordx4 s[16:19], s[0:1], 0xa0
	s_mov_b32 s15, 1
	s_mov_b64 s[12:13], 0
	s_waitcnt lgkmcnt(0)
	s_add_u32 s8, s18, 0x4200
	s_addc_u32 s9, s19, 0
	s_branch .LBB0_72

.LBB0_81:
	s_or_b64 exec, exec, s[6:7]
	s_waitcnt vmcnt(0)
	s_waitcnt vmcnt(0)

.LBB0_406:
	s_or_b64 exec, exec, s[4:5]
	v_cvt_f32_u32_e32 v5, v3
	s_waitcnt vmcnt(0)
	v_readfirstlane_b32 s2, v4
	v_sub_u32_e32 v4, 0, v3
	v_rcp_iflag_f32_e32 v5, v5
	v_add_u32_e32 v6, s2, v0
	v_mul_f32_e32 v5, 0x4f7ffffe, v5
	v_cvt_u32_f32_e32 v5, v5
	v_mul_lo_u32 v0, v4, v5
	v_mul_hi_u32 v0, v5, v0
	v_add_u32_e32 v0, v5, v0
	v_mul_hi_u32 v0, v6, v0
	v_mul_lo_u32 v4, v0, v3
	v_sub_u32_e32 v4, v6, v4
	v_add_u32_e32 v5, 1, v0
	v_cmp_ge_u32_e32 vcc, v4, v3
	s_nop 1
	v_cndmask_b32_e32 v0, v0, v5, vcc
	v_sub_u32_e32 v5, v4, v3
	v_cndmask_b32_e32 v4, v4, v5, vcc
	v_add_u32_e32 v5, 1, v0
	v_cmp_ge_u32_e32 vcc, v4, v3
	v_add_u32_e32 v4, 1, v6
	s_nop 0
	v_cndmask_b32_e32 v0, v0, v5, vcc
	v_mul_lo_u32 v5, v3, v0
	v_add_u32_e32 v3, v5, v3
	v_cmp_ne_u32_e32 vcc, v4, v3
	s_and_saveexec_b64 s[2:3], vcc
	s_xor_b64 s[2:3], exec, s[2:3]
	s_cbranch_execz .LBB0_420
	s_add_i32 s86, s20, 0x900
	s_lshl_b64 s[4:5], s[86:87], 2
	v_readlane_b32 s6, v252, 44
	v_readlane_b32 s7, v252, 45
	s_add_u32 s6, s6, s4
	s_addc_u32 s7, s7, s5
	s_waitcnt lgkmcnt(0)
	s_nop 1
	buffer_inv sc1
	global_load_dword v2, v1, s[6:7] sc1
	s_waitcnt vmcnt(0)
	v_cmp_eq_u32_e32 vcc, v2, v0
	s_and_saveexec_b64 s[4:5], vcc
	s_cbranch_execz .LBB0_419
	s_mov_b32 s21, 1
	s_mov_b64 s[8:9], 0
	s_branch .LBB0_410

.LBB0_419:
	s_or_b64 exec, exec, s[4:5]
	s_waitcnt vmcnt(0)
	s_waitcnt vmcnt(0)

.LBB0_1268:
	s_or_b64 exec, exec, s[6:7]
	v_cvt_f32_u32_e32 v5, v3
	s_waitcnt vmcnt(0)
	v_readfirstlane_b32 s4, v4
	v_sub_u32_e32 v4, 0, v3
	v_rcp_iflag_f32_e32 v5, v5
	v_add_u32_e32 v6, s4, v0
	v_mul_f32_e32 v5, 0x4f7ffffe, v5
	v_cvt_u32_f32_e32 v5, v5
	v_mul_lo_u32 v0, v4, v5
	v_mul_hi_u32 v0, v5, v0
	v_add_u32_e32 v0, v5, v0
	v_mul_hi_u32 v0, v6, v0
	v_mul_lo_u32 v4, v0, v3
	v_sub_u32_e32 v4, v6, v4
	v_add_u32_e32 v5, 1, v0
	v_cmp_ge_u32_e32 vcc, v4, v3
	s_nop 1
	v_cndmask_b32_e32 v0, v0, v5, vcc
	v_sub_u32_e32 v5, v4, v3
	v_cndmask_b32_e32 v4, v4, v5, vcc
	v_add_u32_e32 v5, 1, v0
	v_cmp_ge_u32_e32 vcc, v4, v3
	v_add_u32_e32 v4, 1, v6
	s_nop 0
	v_cndmask_b32_e32 v0, v0, v5, vcc
	v_mul_lo_u32 v5, v3, v0
	v_add_u32_e32 v3, v5, v3
	v_cmp_ne_u32_e32 vcc, v4, v3
	s_and_saveexec_b64 s[4:5], vcc
	s_xor_b64 s[4:5], exec, s[4:5]
	s_cbranch_execz .LBB0_1282
	s_add_i32 s86, s20, 0x900
	s_lshl_b64 s[6:7], s[86:87], 2
	v_readlane_b32 s8, v252, 44
	v_readlane_b32 s9, v252, 45
	s_add_u32 s8, s8, s6
	s_addc_u32 s9, s9, s7
	s_waitcnt lgkmcnt(0)
	s_nop 1
	buffer_inv sc1
	global_load_dword v2, v1, s[8:9] sc1
	s_waitcnt vmcnt(0)
	v_cmp_eq_u32_e32 vcc, v2, v0
	s_and_saveexec_b64 s[6:7], vcc
	s_cbranch_execz .LBB0_1281
	s_mov_b32 s21, 1
	s_mov_b64 s[10:11], 0
	s_branch .LBB0_1272
